# all LDS-DMA loads in the in-proj and FF1 K-loops use scalar base + lane offset (no 64-bit VALU address adds left)
# speedup vs baseline: 1.0214x; 1.0079x over previous
; #define PG8_STAGE(bufoff, gbase, voff) do { _Pragma("unroll") for (int _i = 0; _i < 2; ++_i) \
;         __builtin_amdgcn_global_load_lds((const unsigned*)((const char*)(gbase) + (voff)[_i]), (LAS unsigned*)(lds + (bufoff) + ldsw + _i * 8192), 16, 0, 0); } while (0)
; #define PG8_LDA(dst, b, h) do { _Pragma("unroll") for (int m = 0; m < 4; ++m) _Pragma("unroll") for (int k = 0; k < 2; ++k) dst[m][k] = *(const LAS bf16x8*)(lds + PG8_SA(b, h) + aoff + m * 2048 + k * 1024); } while (0)
; #define PG8_LDB(dst, b, h) do { _Pragma("unroll") for (int n = 0; n < 2; ++n) _Pragma("unroll") for (int k = 0; k < 2; ++k) dst[n][k] = *(const LAS bf16x8*)(lds + PG8_SB(b, h) + boff + n * 2048 + k * 1024); } while (0)
; #define PG8_MMA(ai, bj, At, Bt) do { __builtin_amdgcn_s_setprio(1); _Pragma("unroll") for (int m = 0; m < 4; ++m) _Pragma("unroll") for (int n = 0; n < 2; ++n) _Pragma("unroll") for (int k = 0; k < 2; ++k) \
;         acc[ai][bj][m][n] = __builtin_amdgcn_mfma_f32_16x16x32_bf16(Bt[n][k], At[m][k], acc[ai][bj][m][n], 0, 0, 0); __builtin_amdgcn_s_setprio(0); } while (0)
; #define PG8_BAR __builtin_amdgcn_s_barrier()
; template <class Epi, class Sched>
; __device__ __forceinline__ void gemm_phase(LAS unsigned char* lds, const Gemm g, const Sched& S, const Epi& E) {
;     ...
;             const bool last = (t == nt - 2);
;             const char* a1 = cA + (size_t)(t + 1) * kstep;
;             const char* a2 = last ? nA : cA + (size_t)(t + 2) * kstep; const char* b2 = last ? nB : cB + (size_t)(t + 2) * kstep;
;             const char* a3 = a2 + kstep; const char* b3 = b2 + kstep;
;             if (last && has_next) S.a_ready(nxt);
;             PG8_LDB(B0, 0, 0); PG8_SCHED; PG8_LDA(At, 0, 0); PG8_STAGE(PG8_SA(1, 1), a1 + hstep, voffA);
;             PG8_WAIT_L(8); PG8_BAR; PG8_WAIT_L(0); PG8_MMA(0, 0, At, B0); PG8_BAR; PG8_SCHED;
;             PG8_LDB(B1, 0, 1); PG8_STAGE(PG8_SB(0, 0), b2, voffB);
;             PG8_BAR; PG8_WAIT_L(0); PG8_MMA(0, 1, At, B1); PG8_BAR;
;             PG8_LDA(At, 0, 1); PG8_STAGE(PG8_SA(0, 0), a2, voffA);
;             PG8_BAR; PG8_WAIT_L(0); PG8_MMA(1, 0, At, B0); PG8_BAR; PG8_SCHED;
;             PG8_STAGE(PG8_SB(0, 1), b2 + hstep, voffB);
;             PG8_WAIT_V(6); PG8_BAR; PG8_MMA(1, 1, At, B1); PG8_BAR;
;             PG8_LDB(B0, 1, 0); PG8_SCHED; PG8_LDA(At, 1, 0); PG8_STAGE(PG8_SA(0, 1), a2 + hstep, voffA);
.LBB0_342:
	s_nop 0
	v_add_u32_e32 v158, s42, v147
	ds_read_b128 v[142:145], v158
	ds_read_b128 v[150:153], v158 offset:1024
	ds_read_b128 v[154:157], v158 offset:2048
	ds_read_b128 v[158:161], v158 offset:3072
	s_add_u32 s18, s16, 0xfff80080
	s_addc_u32 s19, s17, -1
	s_cmp_eq_u32 s38, 28
	s_cselect_b32 s21, s11, s19
	s_cselect_b32 s20, s34, s18
	s_cselect_b32 s19, s9, s37
	s_cselect_b32 s18, s35, s36
	s_add_i32 m0, s24, 0xc000
	ds_read_b128 v[162:165], v149
	ds_read_b128 v[166:169], v149 offset:1024
	ds_read_b128 v[170:173], v149 offset:2048
	ds_read_b128 v[174:177], v149 offset:3072
	ds_read_b128 v[178:181], v149 offset:4096
	ds_read_b128 v[182:185], v149 offset:5120
	ds_read_b128 v[186:189], v149 offset:6144
	ds_read_b128 v[190:193], v149 offset:7168
	global_load_lds_dwordx4 v138, s[16:17]
	s_add_i32 m0, s24, 0xe000
	s_nop 0
	global_load_lds_dwordx4 v140, s[16:17]
	s_waitcnt lgkmcnt(8)
	s_barrier
	s_waitcnt lgkmcnt(0)
	v_mfma_f32_16x16x32_bf16 v[126:129], v[142:145], v[162:165], v[126:129]
	v_mfma_f32_16x16x32_bf16 v[122:125], v[154:157], v[162:165], v[122:125]
	v_mfma_f32_16x16x32_bf16 v[114:117], v[142:145], v[170:173], v[114:117]
	v_mfma_f32_16x16x32_bf16 v[106:109], v[154:157], v[170:173], v[106:109]
	v_mfma_f32_16x16x32_bf16 v[98:101], v[142:145], v[178:181], v[98:101]
	v_mfma_f32_16x16x32_bf16 v[90:93], v[154:157], v[178:181], v[90:93]
	v_mfma_f32_16x16x32_bf16 v[82:85], v[142:145], v[186:189], v[82:85]
	v_mfma_f32_16x16x32_bf16 v[74:77], v[154:157], v[186:189], v[74:77]
	v_mfma_f32_16x16x32_bf16 v[126:129], v[150:153], v[166:169], v[126:129]
	v_mfma_f32_16x16x32_bf16 v[122:125], v[158:161], v[166:169], v[122:125]
	v_mfma_f32_16x16x32_bf16 v[114:117], v[150:153], v[174:177], v[114:117]
	v_mfma_f32_16x16x32_bf16 v[106:109], v[158:161], v[174:177], v[106:109]
	v_mfma_f32_16x16x32_bf16 v[98:101], v[150:153], v[182:185], v[98:101]
	v_mfma_f32_16x16x32_bf16 v[90:93], v[158:161], v[182:185], v[90:93]
	v_mfma_f32_16x16x32_bf16 v[82:85], v[150:153], v[190:193], v[82:85]
	v_mfma_f32_16x16x32_bf16 v[74:77], v[158:161], v[190:193], v[74:77]
	s_barrier
	s_add_i32 s39, 0, 0x14000
	s_add_i32 s40, s42, s23
	v_add_u32_e32 v206, s39, v147
	s_mov_b32 m0, s40
	ds_read_b128 v[194:197], v206
	ds_read_b128 v[198:201], v206 offset:1024
	ds_read_b128 v[202:205], v206 offset:2048
	ds_read_b128 v[206:209], v206 offset:3072
	global_load_lds_dwordx4 v0, s[18:19]
	s_add_i32 m0, s40, 0x2000
	s_nop 0
	global_load_lds_dwordx4 v130, s[18:19]
	s_barrier
	s_waitcnt lgkmcnt(0)
	v_mfma_f32_16x16x32_bf16 v[118:121], v[194:197], v[162:165], v[118:121]
	v_mfma_f32_16x16x32_bf16 v[110:113], v[202:205], v[162:165], v[110:113]
	v_mfma_f32_16x16x32_bf16 v[102:105], v[194:197], v[170:173], v[102:105]
	v_mfma_f32_16x16x32_bf16 v[94:97], v[202:205], v[170:173], v[94:97]
	v_mfma_f32_16x16x32_bf16 v[86:89], v[194:197], v[178:181], v[86:89]
	v_mfma_f32_16x16x32_bf16 v[78:81], v[202:205], v[178:181], v[78:81]
	v_mfma_f32_16x16x32_bf16 v[70:73], v[194:197], v[186:189], v[70:73]
	v_mfma_f32_16x16x32_bf16 v[66:69], v[202:205], v[186:189], v[66:69]
	v_mfma_f32_16x16x32_bf16 v[118:121], v[198:201], v[166:169], v[118:121]
	v_mfma_f32_16x16x32_bf16 v[110:113], v[206:209], v[166:169], v[110:113]
	v_mfma_f32_16x16x32_bf16 v[102:105], v[198:201], v[174:177], v[102:105]
	v_mfma_f32_16x16x32_bf16 v[94:97], v[206:209], v[174:177], v[94:97]
	v_mfma_f32_16x16x32_bf16 v[86:89], v[198:201], v[182:185], v[86:89]
	v_mfma_f32_16x16x32_bf16 v[78:81], v[206:209], v[182:185], v[78:81]
	v_mfma_f32_16x16x32_bf16 v[70:73], v[198:201], v[190:193], v[70:73]
	v_mfma_f32_16x16x32_bf16 v[66:69], v[206:209], v[190:193], v[66:69]
	s_mov_b32 m0, s24
	s_add_u32 s44, s20, 0x80
	s_addc_u32 s45, s21, 0
	s_barrier
	ds_read_b128 v[162:165], v149 offset:16384
	ds_read_b128 v[166:169], v149 offset:17408
	ds_read_b128 v[170:173], v149 offset:18432
	ds_read_b128 v[174:177], v149 offset:19456
	ds_read_b128 v[178:181], v149 offset:20480
	ds_read_b128 v[182:185], v149 offset:21504
	ds_read_b128 v[186:189], v149 offset:22528
	ds_read_b128 v[190:193], v149 offset:23552
	global_load_lds_dwordx4 v134, s[20:21]
	s_mov_b32 m0, s25
	s_nop 0
	global_load_lds_dwordx4 v132, s[20:21]
	s_barrier
	s_waitcnt lgkmcnt(0)
	v_mfma_f32_16x16x32_bf16 v[62:65], v[142:145], v[162:165], v[62:65]
	v_mfma_f32_16x16x32_bf16 v[58:61], v[154:157], v[162:165], v[58:61]
	v_mfma_f32_16x16x32_bf16 v[50:53], v[142:145], v[170:173], v[50:53]
	v_mfma_f32_16x16x32_bf16 v[42:45], v[154:157], v[170:173], v[42:45]
	v_mfma_f32_16x16x32_bf16 v[34:37], v[142:145], v[178:181], v[34:37]
	v_mfma_f32_16x16x32_bf16 v[26:29], v[154:157], v[178:181], v[26:29]
	v_mfma_f32_16x16x32_bf16 v[18:21], v[142:145], v[186:189], v[18:21]
	v_mfma_f32_16x16x32_bf16 v[10:13], v[154:157], v[186:189], v[10:13]
	v_mfma_f32_16x16x32_bf16 v[62:65], v[150:153], v[166:169], v[62:65]
	v_mfma_f32_16x16x32_bf16 v[58:61], v[158:161], v[166:169], v[58:61]
	v_mfma_f32_16x16x32_bf16 v[50:53], v[150:153], v[174:177], v[50:53]
	v_mfma_f32_16x16x32_bf16 v[42:45], v[158:161], v[174:177], v[42:45]
	v_mfma_f32_16x16x32_bf16 v[34:37], v[150:153], v[182:185], v[34:37]
	v_mfma_f32_16x16x32_bf16 v[26:29], v[158:161], v[182:185], v[26:29]
	v_mfma_f32_16x16x32_bf16 v[18:21], v[150:153], v[190:193], v[18:21]
	v_mfma_f32_16x16x32_bf16 v[10:13], v[158:161], v[190:193], v[10:13]
	s_barrier
	s_add_u32 s40, s18, 0x80000
	s_addc_u32 s41, s19, 0
	s_add_i32 s39, s39, s23
	s_mov_b32 m0, s39
	s_nop 0
	global_load_lds_dwordx4 v0, s[40:41]
	s_add_i32 m0, s39, 0x2000
	s_nop 0
	global_load_lds_dwordx4 v130, s[40:41]
	s_waitcnt vmcnt(6)
	s_barrier
; #define PG8_STAGE(bufoff, gbase, voff) do { _Pragma("unroll") for (int _i = 0; _i < 2; ++_i) \
;         __builtin_amdgcn_global_load_lds((const unsigned*)((const char*)(gbase) + (voff)[_i]), (LAS unsigned*)(lds + (bufoff) + ldsw + _i * 8192), 16, 0, 0); } while (0)
; #define PG8_LDA(dst, b, h) do { _Pragma("unroll") for (int m = 0; m < 4; ++m) _Pragma("unroll") for (int k = 0; k < 2; ++k) dst[m][k] = *(const LAS bf16x8*)(lds + PG8_SA(b, h) + aoff + m * 2048 + k * 1024); } while (0)
; #define PG8_LDB(dst, b, h) do { _Pragma("unroll") for (int n = 0; n < 2; ++n) _Pragma("unroll") for (int k = 0; k < 2; ++k) dst[n][k] = *(const LAS bf16x8*)(lds + PG8_SB(b, h) + boff + n * 2048 + k * 1024); } while (0)
; #define PG8_MMA(ai, bj, At, Bt) do { __builtin_amdgcn_s_setprio(1); _Pragma("unroll") for (int m = 0; m < 4; ++m) _Pragma("unroll") for (int n = 0; n < 2; ++n) _Pragma("unroll") for (int k = 0; k < 2; ++k) \
;         acc[ai][bj][m][n] = __builtin_amdgcn_mfma_f32_16x16x32_bf16(Bt[n][k], At[m][k], acc[ai][bj][m][n], 0, 0, 0); __builtin_amdgcn_s_setprio(0); } while (0)
; #define PG8_WAIT_V(n) asm volatile("s_waitcnt vmcnt(" #n ")" ::: "memory")
; #define PG8_WAIT_L(n) asm volatile("s_waitcnt lgkmcnt(" #n ")" ::: "memory")
; #define PG8_BAR __builtin_amdgcn_s_barrier()
; #define PG8_SCHED __builtin_amdgcn_sched_barrier(0)
; template <class Epi, class Sched>
; __device__ __forceinline__ void gemm_phase(LAS unsigned char* lds, const Gemm g, const Sched& S, const Epi& E) {
;     ...
;             PG8_WAIT_V(6); PG8_BAR; PG8_MMA(1, 1, At, B1); PG8_BAR;
;             PG8_LDB(B0, 1, 0); PG8_SCHED; PG8_LDA(At, 1, 0); PG8_STAGE(PG8_SA(0, 1), a2 + hstep, voffA);
;             PG8_WAIT_L(8); PG8_BAR; PG8_WAIT_L(0); PG8_MMA(0, 0, At, B0); PG8_BAR; PG8_SCHED;
;             PG8_LDB(B1, 1, 1); PG8_STAGE(PG8_SB(1, 0), b3, voffB);
;             PG8_BAR; PG8_WAIT_L(0); PG8_MMA(0, 1, At, B1); PG8_BAR;
;             PG8_LDA(At, 1, 1); PG8_STAGE(PG8_SA(1, 0), a3, voffA);
	v_mfma_f32_16x16x32_bf16 v[54:57], v[194:197], v[162:165], v[54:57]
	v_mfma_f32_16x16x32_bf16 v[46:49], v[202:205], v[162:165], v[46:49]
	v_mfma_f32_16x16x32_bf16 v[38:41], v[194:197], v[170:173], v[38:41]
	v_mfma_f32_16x16x32_bf16 v[30:33], v[202:205], v[170:173], v[30:33]
	v_mfma_f32_16x16x32_bf16 v[22:25], v[194:197], v[178:181], v[22:25]
	v_mfma_f32_16x16x32_bf16 v[14:17], v[202:205], v[178:181], v[14:17]
	v_mfma_f32_16x16x32_bf16 v[6:9], v[194:197], v[186:189], v[6:9]
	v_mfma_f32_16x16x32_bf16 v[2:5], v[202:205], v[186:189], v[2:5]
	v_mfma_f32_16x16x32_bf16 v[54:57], v[198:201], v[166:169], v[54:57]
	v_mfma_f32_16x16x32_bf16 v[46:49], v[206:209], v[166:169], v[46:49]
	v_mfma_f32_16x16x32_bf16 v[38:41], v[198:201], v[174:177], v[38:41]
	v_mfma_f32_16x16x32_bf16 v[30:33], v[206:209], v[174:177], v[30:33]
	v_mfma_f32_16x16x32_bf16 v[22:25], v[198:201], v[182:185], v[22:25]
	v_mfma_f32_16x16x32_bf16 v[14:17], v[206:209], v[182:185], v[14:17]
	v_mfma_f32_16x16x32_bf16 v[6:9], v[198:201], v[190:193], v[6:9]
	v_mfma_f32_16x16x32_bf16 v[2:5], v[206:209], v[190:193], v[2:5]
	s_add_i32 s39, 0, 0x18000
	v_add_u32_e32 v158, s39, v147
	s_barrier
	ds_read_b128 v[142:145], v158
	ds_read_b128 v[150:153], v158 offset:1024
	ds_read_b128 v[154:157], v158 offset:2048
	ds_read_b128 v[158:161], v158 offset:3072
	s_add_u32 s20, s20, 0x80000
	s_addc_u32 s21, s21, 0
	s_mov_b32 m0, s26
	ds_read_b128 v[162:165], v149 offset:32768
	ds_read_b128 v[166:169], v149 offset:33792
	ds_read_b128 v[170:173], v149 offset:34816
	ds_read_b128 v[174:177], v149 offset:35840
	ds_read_b128 v[178:181], v149 offset:36864
	ds_read_b128 v[182:185], v149 offset:37888
	ds_read_b128 v[186:189], v149 offset:38912
	ds_read_b128 v[190:193], v149 offset:39936
	global_load_lds_dwordx4 v134, s[20:21]
	s_mov_b32 m0, s27
	s_nop 0
	global_load_lds_dwordx4 v132, s[20:21]
	s_waitcnt lgkmcnt(8)
	s_barrier
	s_waitcnt lgkmcnt(0)
	v_mfma_f32_16x16x32_bf16 v[126:129], v[142:145], v[162:165], v[126:129]
	v_mfma_f32_16x16x32_bf16 v[122:125], v[154:157], v[162:165], v[122:125]
	v_mfma_f32_16x16x32_bf16 v[114:117], v[142:145], v[170:173], v[114:117]
	v_mfma_f32_16x16x32_bf16 v[106:109], v[154:157], v[170:173], v[106:109]
	v_mfma_f32_16x16x32_bf16 v[98:101], v[142:145], v[178:181], v[98:101]
	v_mfma_f32_16x16x32_bf16 v[90:93], v[154:157], v[178:181], v[90:93]
	v_mfma_f32_16x16x32_bf16 v[82:85], v[142:145], v[186:189], v[82:85]
	v_mfma_f32_16x16x32_bf16 v[74:77], v[154:157], v[186:189], v[74:77]
	v_mfma_f32_16x16x32_bf16 v[126:129], v[150:153], v[166:169], v[126:129]
	v_mfma_f32_16x16x32_bf16 v[122:125], v[158:161], v[166:169], v[122:125]
	v_mfma_f32_16x16x32_bf16 v[114:117], v[150:153], v[174:177], v[114:117]
	v_mfma_f32_16x16x32_bf16 v[106:109], v[158:161], v[174:177], v[106:109]
	v_mfma_f32_16x16x32_bf16 v[98:101], v[150:153], v[182:185], v[98:101]
	v_mfma_f32_16x16x32_bf16 v[90:93], v[158:161], v[182:185], v[90:93]
	v_mfma_f32_16x16x32_bf16 v[82:85], v[150:153], v[190:193], v[82:85]
	v_mfma_f32_16x16x32_bf16 v[74:77], v[158:161], v[190:193], v[74:77]
	s_barrier
	s_add_i32 s20, 0, 0x1c000
	s_add_i32 s21, s39, s23
	v_add_u32_e32 v206, s20, v147
	s_add_u32 s40, s18, 0x80
	s_addc_u32 s41, s19, 0
	s_mov_b32 m0, s21
	ds_read_b128 v[194:197], v206
	ds_read_b128 v[198:201], v206 offset:1024
	ds_read_b128 v[202:205], v206 offset:2048
	ds_read_b128 v[206:209], v206 offset:3072
	global_load_lds_dwordx4 v0, s[40:41]
	s_add_i32 m0, s21, 0x2000
	s_nop 0
	global_load_lds_dwordx4 v130, s[40:41]
	s_barrier
	s_waitcnt lgkmcnt(0)
	v_mfma_f32_16x16x32_bf16 v[118:121], v[194:197], v[162:165], v[118:121]
	v_mfma_f32_16x16x32_bf16 v[110:113], v[202:205], v[162:165], v[110:113]
	v_mfma_f32_16x16x32_bf16 v[102:105], v[194:197], v[170:173], v[102:105]
	v_mfma_f32_16x16x32_bf16 v[94:97], v[202:205], v[170:173], v[94:97]
	v_mfma_f32_16x16x32_bf16 v[86:89], v[194:197], v[178:181], v[86:89]
	v_mfma_f32_16x16x32_bf16 v[78:81], v[202:205], v[178:181], v[78:81]
	v_mfma_f32_16x16x32_bf16 v[70:73], v[194:197], v[186:189], v[70:73]
	v_mfma_f32_16x16x32_bf16 v[66:69], v[202:205], v[186:189], v[66:69]
	v_mfma_f32_16x16x32_bf16 v[118:121], v[198:201], v[166:169], v[118:121]
	v_mfma_f32_16x16x32_bf16 v[110:113], v[206:209], v[166:169], v[110:113]
	v_mfma_f32_16x16x32_bf16 v[102:105], v[198:201], v[174:177], v[102:105]
	v_mfma_f32_16x16x32_bf16 v[94:97], v[206:209], v[174:177], v[94:97]
	v_mfma_f32_16x16x32_bf16 v[86:89], v[198:201], v[182:185], v[86:89]
	v_mfma_f32_16x16x32_bf16 v[78:81], v[206:209], v[182:185], v[78:81]
	v_mfma_f32_16x16x32_bf16 v[70:73], v[198:201], v[190:193], v[70:73]
	v_mfma_f32_16x16x32_bf16 v[66:69], v[206:209], v[190:193], v[66:69]
	s_mov_b32 m0, s28
	s_barrier
; #define PG8_STAGE(bufoff, gbase, voff) do { _Pragma("unroll") for (int _i = 0; _i < 2; ++_i) \
;         __builtin_amdgcn_global_load_lds((const unsigned*)((const char*)(gbase) + (voff)[_i]), (LAS unsigned*)(lds + (bufoff) + ldsw + _i * 8192), 16, 0, 0); } while (0)
; #define PG8_LDA(dst, b, h) do { _Pragma("unroll") for (int m = 0; m < 4; ++m) _Pragma("unroll") for (int k = 0; k < 2; ++k) dst[m][k] = *(const LAS bf16x8*)(lds + PG8_SA(b, h) + aoff + m * 2048 + k * 1024); } while (0)
; #define PG8_LDB(dst, b, h) do { _Pragma("unroll") for (int n = 0; n < 2; ++n) _Pragma("unroll") for (int k = 0; k < 2; ++k) dst[n][k] = *(const LAS bf16x8*)(lds + PG8_SB(b, h) + boff + n * 2048 + k * 1024); } while (0)
; #define PG8_WAIT_V(n) asm volatile("s_waitcnt vmcnt(" #n ")" ::: "memory")
; #define PG8_WAIT_L(n) asm volatile("s_waitcnt lgkmcnt(" #n ")" ::: "memory")
; template <class Epi, class Sched>
; __device__ __forceinline__ void gemm_phase(LAS unsigned char* lds, const Gemm g, const Sched& S, const Epi& E) {
;     ...
;             PG8_LDB(B1, 1, 1); PG8_STAGE(PG8_SB(1, 0), b3, voffB);
;             PG8_BAR; PG8_WAIT_L(0); PG8_MMA(0, 1, At, B1); PG8_BAR;
;             PG8_LDA(At, 1, 1); PG8_STAGE(PG8_SA(1, 0), a3, voffA);
;             PG8_BAR; PG8_WAIT_L(0); PG8_MMA(1, 0, At, B0); PG8_BAR; PG8_SCHED;
;             PG8_STAGE(PG8_SB(1, 1), b3 + hstep, voffB);
;             PG8_WAIT_V(6); PG8_BAR; PG8_MMA(1, 1, At, B1); PG8_BAR;
;     __device__ __forceinline__ void operator()(const f32x4 (&acc)[2][2][4][2], const pg8::Unit& u, int wr, int wc, int fr, int fq) const {
;         const int row0 = u.pm * 256 + wr * 64 + fr; const int col0 = u.pn * 256 + wc * 32 + 8 * fq;
; #pragma unroll
;         for (int ai = 0; ai < 2; ++ai)
; #pragma unroll
;             for (int m = 0; m < 4; ++m) { const int row = row0 + ai * 128 + m * 16; bf16_t* rowp = O + (size_t)row * ldc + col0;
; #pragma unroll
;                 for (int bj = 0; bj < 2; ++bj) { f32x4 v0 = acc[ai][bj][m][0], v1 = acc[ai][bj][m][1];
;                     if (ACT == 1) {
; #pragma unroll
;                         for (int j = 0; j < 4; ++j) { float a = fmaxf(v0[j], 0.f), b = fmaxf(v1[j], 0.f); v0[j] = a * a; v1[j] = b * b; } }
;                     if (ACT == 0) { if (u.pn == (C_G / 256) && bj == 0 && wc == 0 && fq < 2) { float* gp = gate + (size_t)row * 16 + 8 * fq; *(f32x4*)gp = v0; *(f32x4*)(gp + 4) = v1; } }
	ds_read_b128 v[162:165], v149 offset:49152
	ds_read_b128 v[166:169], v149 offset:50176
	ds_read_b128 v[170:173], v149 offset:51200
	ds_read_b128 v[174:177], v149 offset:52224
	ds_read_b128 v[178:181], v149 offset:53248
	ds_read_b128 v[182:185], v149 offset:54272
	ds_read_b128 v[186:189], v149 offset:55296
	ds_read_b128 v[190:193], v149 offset:56320
	global_load_lds_dwordx4 v134, s[44:45]
	s_mov_b32 m0, s29
	s_nop 0
	global_load_lds_dwordx4 v132, s[44:45]
	s_barrier
	s_waitcnt lgkmcnt(0)
	v_mfma_f32_16x16x32_bf16 v[62:65], v[142:145], v[162:165], v[62:65]
	v_mfma_f32_16x16x32_bf16 v[58:61], v[154:157], v[162:165], v[58:61]
	v_mfma_f32_16x16x32_bf16 v[50:53], v[142:145], v[170:173], v[50:53]
	v_mfma_f32_16x16x32_bf16 v[42:45], v[154:157], v[170:173], v[42:45]
	v_mfma_f32_16x16x32_bf16 v[34:37], v[142:145], v[178:181], v[34:37]
	v_mfma_f32_16x16x32_bf16 v[26:29], v[154:157], v[178:181], v[26:29]
	v_mfma_f32_16x16x32_bf16 v[18:21], v[142:145], v[186:189], v[18:21]
	v_mfma_f32_16x16x32_bf16 v[10:13], v[154:157], v[186:189], v[10:13]
	v_mfma_f32_16x16x32_bf16 v[62:65], v[150:153], v[166:169], v[62:65]
	v_mfma_f32_16x16x32_bf16 v[58:61], v[158:161], v[166:169], v[58:61]
	v_mfma_f32_16x16x32_bf16 v[50:53], v[150:153], v[174:177], v[50:53]
	v_mfma_f32_16x16x32_bf16 v[42:45], v[158:161], v[174:177], v[42:45]
	v_mfma_f32_16x16x32_bf16 v[34:37], v[150:153], v[182:185], v[34:37]
	v_mfma_f32_16x16x32_bf16 v[26:29], v[158:161], v[182:185], v[26:29]
	v_mfma_f32_16x16x32_bf16 v[18:21], v[150:153], v[190:193], v[18:21]
	v_mfma_f32_16x16x32_bf16 v[10:13], v[158:161], v[190:193], v[10:13]
	s_barrier
	s_add_u32 s18, s18, 0x80080
	s_addc_u32 s19, s19, 0
	s_add_i32 s20, s20, s23
	s_mov_b32 m0, s20
	s_nop 0
	global_load_lds_dwordx4 v0, s[18:19]
	s_add_i32 m0, s20, 0x2000
	s_nop 0
	global_load_lds_dwordx4 v130, s[18:19]
	s_waitcnt vmcnt(6)
	s_barrier
	v_mfma_f32_16x16x32_bf16 v[54:57], v[194:197], v[162:165], v[54:57]
	v_mfma_f32_16x16x32_bf16 v[46:49], v[202:205], v[162:165], v[46:49]
	v_mfma_f32_16x16x32_bf16 v[38:41], v[194:197], v[170:173], v[38:41]
	v_mfma_f32_16x16x32_bf16 v[30:33], v[202:205], v[170:173], v[30:33]
	v_mfma_f32_16x16x32_bf16 v[22:25], v[194:197], v[178:181], v[22:25]
	v_mfma_f32_16x16x32_bf16 v[14:17], v[202:205], v[178:181], v[14:17]
	v_mfma_f32_16x16x32_bf16 v[6:9], v[194:197], v[186:189], v[6:9]
	v_mfma_f32_16x16x32_bf16 v[2:5], v[202:205], v[186:189], v[2:5]
	v_mfma_f32_16x16x32_bf16 v[54:57], v[198:201], v[166:169], v[54:57]
	v_mfma_f32_16x16x32_bf16 v[46:49], v[206:209], v[166:169], v[46:49]
	v_mfma_f32_16x16x32_bf16 v[38:41], v[198:201], v[174:177], v[38:41]
	v_mfma_f32_16x16x32_bf16 v[30:33], v[206:209], v[174:177], v[30:33]
	v_mfma_f32_16x16x32_bf16 v[22:25], v[198:201], v[182:185], v[22:25]
	v_mfma_f32_16x16x32_bf16 v[14:17], v[206:209], v[182:185], v[14:17]
	v_mfma_f32_16x16x32_bf16 v[6:9], v[198:201], v[190:193], v[6:9]
	v_mfma_f32_16x16x32_bf16 v[2:5], v[206:209], v[190:193], v[2:5]
	s_add_i32 s38, s38, 2
	s_add_u32 s16, s16, 0x100
	s_addc_u32 s17, s17, 0
	s_add_u32 s36, s36, 0x100
	s_addc_u32 s37, s37, 0
	s_cmp_gt_u32 s38, 29
	s_barrier
	s_cbranch_scc0 .LBB0_342
	s_cmp_eq_u32 s3, 18
	s_cselect_b64 s[16:17], -1, 0
	v_lshl_add_u32 v142, s31, 8, v146
	s_and_b64 s[16:17], s[6:7], s[16:17]
	v_ashrrev_i32_e32 v143, 31, v142
	s_and_b64 s[16:17], s[16:17], s[0:1]
	s_and_saveexec_b64 s[18:19], s[16:17]
	s_cbranch_execz .LBB0_345
	v_lshlrev_b64 v[144:145], 6, v[142:143]
	v_lshl_add_u64 v[144:145], v[136:137], 0, v[144:145]
	global_store_dwordx4 v[144:145], v[126:129], off
	global_store_dwordx4 v[144:145], v[122:125], off offset:16

; #define PG8_STAGE(bufoff, gbase, voff) do { _Pragma("unroll") for (int _i = 0; _i < 2; ++_i) \
;         __builtin_amdgcn_global_load_lds((const unsigned*)((const char*)(gbase) + (voff)[_i]), (LAS unsigned*)(lds + (bufoff) + ldsw + _i * 8192), 16, 0, 0); } while (0)
; #define PG8_LDA(dst, b, h) do { _Pragma("unroll") for (int m = 0; m < 4; ++m) _Pragma("unroll") for (int k = 0; k < 2; ++k) dst[m][k] = *(const LAS bf16x8*)(lds + PG8_SA(b, h) + aoff + m * 2048 + k * 1024); } while (0)
; #define PG8_LDB(dst, b, h) do { _Pragma("unroll") for (int n = 0; n < 2; ++n) _Pragma("unroll") for (int k = 0; k < 2; ++k) dst[n][k] = *(const LAS bf16x8*)(lds + PG8_SB(b, h) + boff + n * 2048 + k * 1024); } while (0)
; #define PG8_MMA(ai, bj, At, Bt) do { __builtin_amdgcn_s_setprio(1); _Pragma("unroll") for (int m = 0; m < 4; ++m) _Pragma("unroll") for (int n = 0; n < 2; ++n) _Pragma("unroll") for (int k = 0; k < 2; ++k) \
;         acc[ai][bj][m][n] = __builtin_amdgcn_mfma_f32_16x16x32_bf16(Bt[n][k], At[m][k], acc[ai][bj][m][n], 0, 0, 0); __builtin_amdgcn_s_setprio(0); } while (0)
; #define PG8_BAR __builtin_amdgcn_s_barrier()
; template <class Epi, class Sched>
; __device__ __forceinline__ void gemm_phase(LAS unsigned char* lds, const Gemm g, const Sched& S, const Epi& E) {
;     ...
;             const bool last = (t == nt - 2);
;             const char* a1 = cA + (size_t)(t + 1) * kstep;
;             const char* a2 = last ? nA : cA + (size_t)(t + 2) * kstep; const char* b2 = last ? nB : cB + (size_t)(t + 2) * kstep;
;             const char* a3 = a2 + kstep; const char* b3 = b2 + kstep;
;             if (last && has_next) S.a_ready(nxt);
;             PG8_LDB(B0, 0, 0); PG8_SCHED; PG8_LDA(At, 0, 0); PG8_STAGE(PG8_SA(1, 1), a1 + hstep, voffA);
;             PG8_WAIT_L(8); PG8_BAR; PG8_WAIT_L(0); PG8_MMA(0, 0, At, B0); PG8_BAR; PG8_SCHED;
;             PG8_LDB(B1, 0, 1); PG8_STAGE(PG8_SB(0, 0), b2, voffB);
;             PG8_BAR; PG8_WAIT_L(0); PG8_MMA(0, 1, At, B1); PG8_BAR;
;             PG8_LDA(At, 0, 1); PG8_STAGE(PG8_SA(0, 0), a2, voffA);
;             PG8_BAR; PG8_WAIT_L(0); PG8_MMA(1, 0, At, B0); PG8_BAR; PG8_SCHED;
;             PG8_STAGE(PG8_SB(0, 1), b2 + hstep, voffB);
;             PG8_WAIT_V(6); PG8_BAR; PG8_MMA(1, 1, At, B1); PG8_BAR;
;             PG8_LDB(B0, 1, 0); PG8_SCHED; PG8_LDA(At, 1, 0); PG8_STAGE(PG8_SA(0, 1), a2 + hstep, voffA);
.LBB0_1279:
	s_nop 0
	v_add_u32_e32 v140, s47, v143
	ds_read_b128 v[146:149], v140
	ds_read_b128 v[150:153], v140 offset:1024
	ds_read_b128 v[154:157], v140 offset:2048
	ds_read_b128 v[158:161], v140 offset:3072
	s_add_u32 s22, s20, 0xfff80080
	s_addc_u32 s23, s21, -1
	s_cmp_eq_u32 s43, 28
	s_cselect_b32 s25, s3, s23
	s_cselect_b32 s24, s11, s22
	s_cselect_b32 s23, s9, s42
	s_cselect_b32 s22, s40, s41
	s_add_i32 m0, s17, 0xc000
	ds_read_b128 v[162:165], v145
	ds_read_b128 v[166:169], v145 offset:1024
	ds_read_b128 v[170:173], v145 offset:2048
	ds_read_b128 v[174:177], v145 offset:3072
	ds_read_b128 v[178:181], v145 offset:4096
	ds_read_b128 v[182:185], v145 offset:5120
	ds_read_b128 v[186:189], v145 offset:6144
	ds_read_b128 v[190:193], v145 offset:7168
	global_load_lds_dwordx4 v136, s[20:21]
	s_add_i32 m0, s17, 0xe000
	s_nop 0
	global_load_lds_dwordx4 v138, s[20:21]
	s_waitcnt lgkmcnt(8)
	s_barrier
	s_waitcnt lgkmcnt(0)
	v_mfma_f32_16x16x32_bf16 v[126:129], v[146:149], v[162:165], v[126:129]
	v_mfma_f32_16x16x32_bf16 v[122:125], v[154:157], v[162:165], v[122:125]
	v_mfma_f32_16x16x32_bf16 v[110:113], v[146:149], v[170:173], v[110:113]
	v_mfma_f32_16x16x32_bf16 v[106:109], v[154:157], v[170:173], v[106:109]
	v_mfma_f32_16x16x32_bf16 v[94:97], v[146:149], v[178:181], v[94:97]
	v_mfma_f32_16x16x32_bf16 v[90:93], v[154:157], v[178:181], v[90:93]
	v_mfma_f32_16x16x32_bf16 v[78:81], v[146:149], v[186:189], v[78:81]
	v_mfma_f32_16x16x32_bf16 v[74:77], v[154:157], v[186:189], v[74:77]
	v_mfma_f32_16x16x32_bf16 v[126:129], v[150:153], v[166:169], v[126:129]
	v_mfma_f32_16x16x32_bf16 v[122:125], v[158:161], v[166:169], v[122:125]
	v_mfma_f32_16x16x32_bf16 v[110:113], v[150:153], v[174:177], v[110:113]
	v_mfma_f32_16x16x32_bf16 v[106:109], v[158:161], v[174:177], v[106:109]
	v_mfma_f32_16x16x32_bf16 v[94:97], v[150:153], v[182:185], v[94:97]
	v_mfma_f32_16x16x32_bf16 v[90:93], v[158:161], v[182:185], v[90:93]
	v_mfma_f32_16x16x32_bf16 v[78:81], v[150:153], v[190:193], v[78:81]
	v_mfma_f32_16x16x32_bf16 v[74:77], v[158:161], v[190:193], v[74:77]
	s_barrier
	s_add_i32 s46, 0, 0x14000
	v_add_u32_e32 v140, s46, v143
	s_add_i32 s44, s47, s30
	ds_read_b128 v[194:197], v140
	ds_read_b128 v[198:201], v140 offset:1024
	ds_read_b128 v[202:205], v140 offset:2048
	ds_read_b128 v[206:209], v140 offset:3072
	s_mov_b32 m0, s44
	s_nop 0
	global_load_lds_dwordx4 v0, s[22:23]
	s_add_i32 m0, s44, 0x2000
	s_nop 0
	global_load_lds_dwordx4 v130, s[22:23]
	s_barrier
	s_waitcnt lgkmcnt(0)
	v_mfma_f32_16x16x32_bf16 v[118:121], v[194:197], v[162:165], v[118:121]
	v_mfma_f32_16x16x32_bf16 v[114:117], v[202:205], v[162:165], v[114:117]
	v_mfma_f32_16x16x32_bf16 v[102:105], v[194:197], v[170:173], v[102:105]
	v_mfma_f32_16x16x32_bf16 v[98:101], v[202:205], v[170:173], v[98:101]
	v_mfma_f32_16x16x32_bf16 v[86:89], v[194:197], v[178:181], v[86:89]
	v_mfma_f32_16x16x32_bf16 v[82:85], v[202:205], v[178:181], v[82:85]
	v_mfma_f32_16x16x32_bf16 v[70:73], v[194:197], v[186:189], v[70:73]
	v_mfma_f32_16x16x32_bf16 v[66:69], v[202:205], v[186:189], v[66:69]
	v_mfma_f32_16x16x32_bf16 v[118:121], v[198:201], v[166:169], v[118:121]
	v_mfma_f32_16x16x32_bf16 v[114:117], v[206:209], v[166:169], v[114:117]
	v_mfma_f32_16x16x32_bf16 v[102:105], v[198:201], v[174:177], v[102:105]
	v_mfma_f32_16x16x32_bf16 v[98:101], v[206:209], v[174:177], v[98:101]
	v_mfma_f32_16x16x32_bf16 v[86:89], v[198:201], v[182:185], v[86:89]
	v_mfma_f32_16x16x32_bf16 v[82:85], v[206:209], v[182:185], v[82:85]
	v_mfma_f32_16x16x32_bf16 v[70:73], v[198:201], v[190:193], v[70:73]
	v_mfma_f32_16x16x32_bf16 v[66:69], v[206:209], v[190:193], v[66:69]
	s_mov_b32 m0, s17
	s_add_u32 s48, s24, 0x80
	s_addc_u32 s49, s25, 0
	s_barrier
	ds_read_b128 v[162:165], v145 offset:16384
	ds_read_b128 v[166:169], v145 offset:17408
	ds_read_b128 v[170:173], v145 offset:18432
	ds_read_b128 v[174:177], v145 offset:19456
	ds_read_b128 v[178:181], v145 offset:20480
	ds_read_b128 v[182:185], v145 offset:21504
	ds_read_b128 v[186:189], v145 offset:22528
	ds_read_b128 v[190:193], v145 offset:23552
	global_load_lds_dwordx4 v134, s[24:25]
	s_mov_b32 m0, s19
	s_nop 0
	global_load_lds_dwordx4 v132, s[24:25]
	s_barrier
	s_waitcnt lgkmcnt(0)
	v_mfma_f32_16x16x32_bf16 v[62:65], v[146:149], v[162:165], v[62:65]
	v_mfma_f32_16x16x32_bf16 v[58:61], v[154:157], v[162:165], v[58:61]
	v_mfma_f32_16x16x32_bf16 v[46:49], v[146:149], v[170:173], v[46:49]
	v_mfma_f32_16x16x32_bf16 v[42:45], v[154:157], v[170:173], v[42:45]
	v_mfma_f32_16x16x32_bf16 v[30:33], v[146:149], v[178:181], v[30:33]
	v_mfma_f32_16x16x32_bf16 v[26:29], v[154:157], v[178:181], v[26:29]
	v_mfma_f32_16x16x32_bf16 v[14:17], v[146:149], v[186:189], v[14:17]
	v_mfma_f32_16x16x32_bf16 v[10:13], v[154:157], v[186:189], v[10:13]
	v_mfma_f32_16x16x32_bf16 v[62:65], v[150:153], v[166:169], v[62:65]
	v_mfma_f32_16x16x32_bf16 v[58:61], v[158:161], v[166:169], v[58:61]
	v_mfma_f32_16x16x32_bf16 v[46:49], v[150:153], v[174:177], v[46:49]
	v_mfma_f32_16x16x32_bf16 v[42:45], v[158:161], v[174:177], v[42:45]
	v_mfma_f32_16x16x32_bf16 v[30:33], v[150:153], v[182:185], v[30:33]
	v_mfma_f32_16x16x32_bf16 v[26:29], v[158:161], v[182:185], v[26:29]
	v_mfma_f32_16x16x32_bf16 v[14:17], v[150:153], v[190:193], v[14:17]
	v_mfma_f32_16x16x32_bf16 v[10:13], v[158:161], v[190:193], v[10:13]
	s_barrier
	s_add_u32 s44, s22, 0x80000
	s_addc_u32 s45, s23, 0
	s_add_i32 s46, s46, s30
	s_mov_b32 m0, s46
	s_nop 0
	global_load_lds_dwordx4 v0, s[44:45]
	s_add_i32 m0, s46, 0x2000
	s_nop 0
	global_load_lds_dwordx4 v130, s[44:45]
	s_waitcnt vmcnt(6)
	s_barrier
; #define PG8_STAGE(bufoff, gbase, voff) do { _Pragma("unroll") for (int _i = 0; _i < 2; ++_i) \
;         __builtin_amdgcn_global_load_lds((const unsigned*)((const char*)(gbase) + (voff)[_i]), (LAS unsigned*)(lds + (bufoff) + ldsw + _i * 8192), 16, 0, 0); } while (0)
; #define PG8_LDA(dst, b, h) do { _Pragma("unroll") for (int m = 0; m < 4; ++m) _Pragma("unroll") for (int k = 0; k < 2; ++k) dst[m][k] = *(const LAS bf16x8*)(lds + PG8_SA(b, h) + aoff + m * 2048 + k * 1024); } while (0)
; #define PG8_LDB(dst, b, h) do { _Pragma("unroll") for (int n = 0; n < 2; ++n) _Pragma("unroll") for (int k = 0; k < 2; ++k) dst[n][k] = *(const LAS bf16x8*)(lds + PG8_SB(b, h) + boff + n * 2048 + k * 1024); } while (0)
; #define PG8_MMA(ai, bj, At, Bt) do { __builtin_amdgcn_s_setprio(1); _Pragma("unroll") for (int m = 0; m < 4; ++m) _Pragma("unroll") for (int n = 0; n < 2; ++n) _Pragma("unroll") for (int k = 0; k < 2; ++k) \
;         acc[ai][bj][m][n] = __builtin_amdgcn_mfma_f32_16x16x32_bf16(Bt[n][k], At[m][k], acc[ai][bj][m][n], 0, 0, 0); __builtin_amdgcn_s_setprio(0); } while (0)
; #define PG8_WAIT_V(n) asm volatile("s_waitcnt vmcnt(" #n ")" ::: "memory")
; #define PG8_WAIT_L(n) asm volatile("s_waitcnt lgkmcnt(" #n ")" ::: "memory")
; #define PG8_BAR __builtin_amdgcn_s_barrier()
; #define PG8_SCHED __builtin_amdgcn_sched_barrier(0)
; template <class Epi, class Sched>
; __device__ __forceinline__ void gemm_phase(LAS unsigned char* lds, const Gemm g, const Sched& S, const Epi& E) {
;     ...
;             PG8_WAIT_V(6); PG8_BAR; PG8_MMA(1, 1, At, B1); PG8_BAR;
;             PG8_LDB(B0, 1, 0); PG8_SCHED; PG8_LDA(At, 1, 0); PG8_STAGE(PG8_SA(0, 1), a2 + hstep, voffA);
;             PG8_WAIT_L(8); PG8_BAR; PG8_WAIT_L(0); PG8_MMA(0, 0, At, B0); PG8_BAR; PG8_SCHED;
;             PG8_LDB(B1, 1, 1); PG8_STAGE(PG8_SB(1, 0), b3, voffB);
;             PG8_BAR; PG8_WAIT_L(0); PG8_MMA(0, 1, At, B1); PG8_BAR;
;             PG8_LDA(At, 1, 1); PG8_STAGE(PG8_SA(1, 0), a3, voffA);
	v_mfma_f32_16x16x32_bf16 v[54:57], v[194:197], v[162:165], v[54:57]
	v_mfma_f32_16x16x32_bf16 v[50:53], v[202:205], v[162:165], v[50:53]
	v_mfma_f32_16x16x32_bf16 v[38:41], v[194:197], v[170:173], v[38:41]
	v_mfma_f32_16x16x32_bf16 v[34:37], v[202:205], v[170:173], v[34:37]
	v_mfma_f32_16x16x32_bf16 v[22:25], v[194:197], v[178:181], v[22:25]
	v_mfma_f32_16x16x32_bf16 v[18:21], v[202:205], v[178:181], v[18:21]
	v_mfma_f32_16x16x32_bf16 v[6:9], v[194:197], v[186:189], v[6:9]
	v_mfma_f32_16x16x32_bf16 v[2:5], v[202:205], v[186:189], v[2:5]
	v_mfma_f32_16x16x32_bf16 v[54:57], v[198:201], v[166:169], v[54:57]
	v_mfma_f32_16x16x32_bf16 v[50:53], v[206:209], v[166:169], v[50:53]
	v_mfma_f32_16x16x32_bf16 v[38:41], v[198:201], v[174:177], v[38:41]
	v_mfma_f32_16x16x32_bf16 v[34:37], v[206:209], v[174:177], v[34:37]
	v_mfma_f32_16x16x32_bf16 v[22:25], v[198:201], v[182:185], v[22:25]
	v_mfma_f32_16x16x32_bf16 v[18:21], v[206:209], v[182:185], v[18:21]
	v_mfma_f32_16x16x32_bf16 v[6:9], v[198:201], v[190:193], v[6:9]
	v_mfma_f32_16x16x32_bf16 v[2:5], v[206:209], v[190:193], v[2:5]
	s_add_i32 s44, 0, 0x18000
	v_add_u32_e32 v158, s44, v143
	s_barrier
	ds_read_b128 v[146:149], v158
	ds_read_b128 v[150:153], v158 offset:1024
	ds_read_b128 v[154:157], v158 offset:2048
	ds_read_b128 v[158:161], v158 offset:3072
	s_add_u32 s24, s24, 0x80000
	s_addc_u32 s25, s25, 0
	s_mov_b32 m0, s35
	ds_read_b128 v[162:165], v145 offset:32768
	ds_read_b128 v[166:169], v145 offset:33792
	ds_read_b128 v[170:173], v145 offset:34816
	ds_read_b128 v[174:177], v145 offset:35840
	ds_read_b128 v[178:181], v145 offset:36864
	ds_read_b128 v[182:185], v145 offset:37888
	ds_read_b128 v[186:189], v145 offset:38912
	ds_read_b128 v[190:193], v145 offset:39936
	global_load_lds_dwordx4 v134, s[24:25]
	s_mov_b32 m0, s36
	s_nop 0
	global_load_lds_dwordx4 v132, s[24:25]
	s_waitcnt lgkmcnt(8)
	s_barrier
	s_waitcnt lgkmcnt(0)
	v_mfma_f32_16x16x32_bf16 v[126:129], v[146:149], v[162:165], v[126:129]
	v_mfma_f32_16x16x32_bf16 v[122:125], v[154:157], v[162:165], v[122:125]
	v_mfma_f32_16x16x32_bf16 v[110:113], v[146:149], v[170:173], v[110:113]
	v_mfma_f32_16x16x32_bf16 v[106:109], v[154:157], v[170:173], v[106:109]
	v_mfma_f32_16x16x32_bf16 v[94:97], v[146:149], v[178:181], v[94:97]
	v_mfma_f32_16x16x32_bf16 v[90:93], v[154:157], v[178:181], v[90:93]
	v_mfma_f32_16x16x32_bf16 v[78:81], v[146:149], v[186:189], v[78:81]
	v_mfma_f32_16x16x32_bf16 v[74:77], v[154:157], v[186:189], v[74:77]
	v_mfma_f32_16x16x32_bf16 v[126:129], v[150:153], v[166:169], v[126:129]
	v_mfma_f32_16x16x32_bf16 v[122:125], v[158:161], v[166:169], v[122:125]
	v_mfma_f32_16x16x32_bf16 v[110:113], v[150:153], v[174:177], v[110:113]
	v_mfma_f32_16x16x32_bf16 v[106:109], v[158:161], v[174:177], v[106:109]
	v_mfma_f32_16x16x32_bf16 v[94:97], v[150:153], v[182:185], v[94:97]
	v_mfma_f32_16x16x32_bf16 v[90:93], v[158:161], v[182:185], v[90:93]
	v_mfma_f32_16x16x32_bf16 v[78:81], v[150:153], v[190:193], v[78:81]
	v_mfma_f32_16x16x32_bf16 v[74:77], v[158:161], v[190:193], v[74:77]
	s_barrier
	s_add_i32 s24, 0, 0x1c000
	s_add_i32 s25, s44, s30
	v_add_u32_e32 v206, s24, v143
	s_add_u32 s44, s22, 0x80
	s_addc_u32 s45, s23, 0
	s_mov_b32 m0, s25
	ds_read_b128 v[194:197], v206
	ds_read_b128 v[198:201], v206 offset:1024
	ds_read_b128 v[202:205], v206 offset:2048
	ds_read_b128 v[206:209], v206 offset:3072
	global_load_lds_dwordx4 v0, s[44:45]
	s_add_i32 m0, s25, 0x2000
	s_nop 0
	global_load_lds_dwordx4 v130, s[44:45]
	s_barrier
	s_waitcnt lgkmcnt(0)
	v_mfma_f32_16x16x32_bf16 v[118:121], v[194:197], v[162:165], v[118:121]
	v_mfma_f32_16x16x32_bf16 v[114:117], v[202:205], v[162:165], v[114:117]
	v_mfma_f32_16x16x32_bf16 v[102:105], v[194:197], v[170:173], v[102:105]
	v_mfma_f32_16x16x32_bf16 v[98:101], v[202:205], v[170:173], v[98:101]
	v_mfma_f32_16x16x32_bf16 v[86:89], v[194:197], v[178:181], v[86:89]
	v_mfma_f32_16x16x32_bf16 v[82:85], v[202:205], v[178:181], v[82:85]
	v_mfma_f32_16x16x32_bf16 v[70:73], v[194:197], v[186:189], v[70:73]
	v_mfma_f32_16x16x32_bf16 v[66:69], v[202:205], v[186:189], v[66:69]
	v_mfma_f32_16x16x32_bf16 v[118:121], v[198:201], v[166:169], v[118:121]
	v_mfma_f32_16x16x32_bf16 v[114:117], v[206:209], v[166:169], v[114:117]
	v_mfma_f32_16x16x32_bf16 v[102:105], v[198:201], v[174:177], v[102:105]
	v_mfma_f32_16x16x32_bf16 v[98:101], v[206:209], v[174:177], v[98:101]
	v_mfma_f32_16x16x32_bf16 v[86:89], v[198:201], v[182:185], v[86:89]
	v_mfma_f32_16x16x32_bf16 v[82:85], v[206:209], v[182:185], v[82:85]
	v_mfma_f32_16x16x32_bf16 v[70:73], v[198:201], v[190:193], v[70:73]
	v_mfma_f32_16x16x32_bf16 v[66:69], v[206:209], v[190:193], v[66:69]
	s_mov_b32 m0, s37
	s_barrier
	ds_read_b128 v[162:165], v145 offset:49152
	ds_read_b128 v[166:169], v145 offset:50176
	ds_read_b128 v[170:173], v145 offset:51200
	ds_read_b128 v[174:177], v145 offset:52224
	ds_read_b128 v[178:181], v145 offset:53248
	ds_read_b128 v[182:185], v145 offset:54272
	ds_read_b128 v[186:189], v145 offset:55296
	ds_read_b128 v[190:193], v145 offset:56320
	global_load_lds_dwordx4 v134, s[48:49]
	s_mov_b32 m0, s38
	s_nop 0
	global_load_lds_dwordx4 v132, s[48:49]
	s_barrier
; __device__ __forceinline__ unsigned cvt_pk_bf16(float lo, float hi) { f32x2_t v = {lo, hi}; bf16x2_t b = __builtin_convertvector(v, bf16x2_t); return __builtin_bit_cast(unsigned, b); }
; #define PG8_STAGE(bufoff, gbase, voff) do { _Pragma("unroll") for (int _i = 0; _i < 2; ++_i) \
;         __builtin_amdgcn_global_load_lds((const unsigned*)((const char*)(gbase) + (voff)[_i]), (LAS unsigned*)(lds + (bufoff) + ldsw + _i * 8192), 16, 0, 0); } while (0)
; #define PG8_MMA(ai, bj, At, Bt) do { __builtin_amdgcn_s_setprio(1); _Pragma("unroll") for (int m = 0; m < 4; ++m) _Pragma("unroll") for (int n = 0; n < 2; ++n) _Pragma("unroll") for (int k = 0; k < 2; ++k) \
;         acc[ai][bj][m][n] = __builtin_amdgcn_mfma_f32_16x16x32_bf16(Bt[n][k], At[m][k], acc[ai][bj][m][n], 0, 0, 0); __builtin_amdgcn_s_setprio(0); } while (0)
; template <class Epi, class Sched>
; __device__ __forceinline__ void gemm_phase(LAS unsigned char* lds, const Gemm g, const Sched& S, const Epi& E) {
;     ...
;             PG8_BAR; PG8_WAIT_L(0); PG8_MMA(1, 0, At, B0); PG8_BAR; PG8_SCHED;
;             PG8_STAGE(PG8_SB(1, 1), b3 + hstep, voffB);
;             PG8_WAIT_V(6); PG8_BAR; PG8_MMA(1, 1, At, B1); PG8_BAR;
;     __device__ __forceinline__ void operator()(const f32x4 (&acc)[2][2][4][2], const pg8::Unit& u, int wr, int wc, int fr, int fq) const {
;         const int row0 = u.pm * 256 + wr * 64 + fr; const int col0 = u.pn * 256 + wc * 32 + 8 * fq;
; #pragma unroll
;         for (int ai = 0; ai < 2; ++ai)
; #pragma unroll
;             for (int m = 0; m < 4; ++m) { const int row = row0 + ai * 128 + m * 16; bf16_t* rowp = O + (size_t)row * ldc + col0;
; #pragma unroll
;                 for (int bj = 0; bj < 2; ++bj) { f32x4 v0 = acc[ai][bj][m][0], v1 = acc[ai][bj][m][1];
;                     if (ACT == 1) {
; #pragma unroll
;                         for (int j = 0; j < 4; ++j) { float a = fmaxf(v0[j], 0.f), b = fmaxf(v1[j], 0.f); v0[j] = a * a; v1[j] = b * b; } }
;                     if (ACT == 0) { if (u.pn == (C_G / 256) && bj == 0 && wc == 0 && fq < 2) { float* gp = gate + (size_t)row * 16 + 8 * fq; *(f32x4*)gp = v0; *(f32x4*)(gp + 4) = v1; } }
;                     u32x4 w; w.x = cvt_pk_bf16(v0[0], v0[1]); w.y = cvt_pk_bf16(v0[2], v0[3]); w.z = cvt_pk_bf16(v1[0], v1[1]); w.w = cvt_pk_bf16(v1[2], v1[3]);
;                     *(u32x4*)(rowp + bj * 128) = w; } }
	s_waitcnt lgkmcnt(0)
	v_mfma_f32_16x16x32_bf16 v[62:65], v[146:149], v[162:165], v[62:65]
	v_mfma_f32_16x16x32_bf16 v[58:61], v[154:157], v[162:165], v[58:61]
	v_mfma_f32_16x16x32_bf16 v[46:49], v[146:149], v[170:173], v[46:49]
	v_mfma_f32_16x16x32_bf16 v[42:45], v[154:157], v[170:173], v[42:45]
	v_mfma_f32_16x16x32_bf16 v[30:33], v[146:149], v[178:181], v[30:33]
	v_mfma_f32_16x16x32_bf16 v[26:29], v[154:157], v[178:181], v[26:29]
	v_mfma_f32_16x16x32_bf16 v[14:17], v[146:149], v[186:189], v[14:17]
	v_mfma_f32_16x16x32_bf16 v[10:13], v[154:157], v[186:189], v[10:13]
	v_mfma_f32_16x16x32_bf16 v[62:65], v[150:153], v[166:169], v[62:65]
	v_mfma_f32_16x16x32_bf16 v[58:61], v[158:161], v[166:169], v[58:61]
	v_mfma_f32_16x16x32_bf16 v[46:49], v[150:153], v[174:177], v[46:49]
	v_mfma_f32_16x16x32_bf16 v[42:45], v[158:161], v[174:177], v[42:45]
	v_mfma_f32_16x16x32_bf16 v[30:33], v[150:153], v[182:185], v[30:33]
	v_mfma_f32_16x16x32_bf16 v[26:29], v[158:161], v[182:185], v[26:29]
	v_mfma_f32_16x16x32_bf16 v[14:17], v[150:153], v[190:193], v[14:17]
	v_mfma_f32_16x16x32_bf16 v[10:13], v[158:161], v[190:193], v[10:13]
	s_barrier
	s_add_u32 s22, s22, 0x80080
	s_addc_u32 s23, s23, 0
	s_add_i32 s24, s24, s30
	s_mov_b32 m0, s24
	s_nop 0
	global_load_lds_dwordx4 v0, s[22:23]
	s_add_i32 m0, s24, 0x2000
	s_nop 0
	global_load_lds_dwordx4 v130, s[22:23]
	s_waitcnt vmcnt(6)
	s_barrier
	v_mfma_f32_16x16x32_bf16 v[54:57], v[194:197], v[162:165], v[54:57]
	v_mfma_f32_16x16x32_bf16 v[50:53], v[202:205], v[162:165], v[50:53]
	v_mfma_f32_16x16x32_bf16 v[38:41], v[194:197], v[170:173], v[38:41]
	v_mfma_f32_16x16x32_bf16 v[34:37], v[202:205], v[170:173], v[34:37]
	v_mfma_f32_16x16x32_bf16 v[22:25], v[194:197], v[178:181], v[22:25]
	v_mfma_f32_16x16x32_bf16 v[18:21], v[202:205], v[178:181], v[18:21]
	v_mfma_f32_16x16x32_bf16 v[6:9], v[194:197], v[186:189], v[6:9]
	v_mfma_f32_16x16x32_bf16 v[2:5], v[202:205], v[186:189], v[2:5]
	v_mfma_f32_16x16x32_bf16 v[54:57], v[198:201], v[166:169], v[54:57]
	v_mfma_f32_16x16x32_bf16 v[50:53], v[206:209], v[166:169], v[50:53]
	v_mfma_f32_16x16x32_bf16 v[38:41], v[198:201], v[174:177], v[38:41]
	v_mfma_f32_16x16x32_bf16 v[34:37], v[206:209], v[174:177], v[34:37]
	v_mfma_f32_16x16x32_bf16 v[22:25], v[198:201], v[182:185], v[22:25]
	v_mfma_f32_16x16x32_bf16 v[18:21], v[206:209], v[182:185], v[18:21]
	v_mfma_f32_16x16x32_bf16 v[6:9], v[198:201], v[190:193], v[6:9]
	v_mfma_f32_16x16x32_bf16 v[2:5], v[206:209], v[190:193], v[2:5]
	s_add_i32 s43, s43, 2
	s_add_u32 s20, s20, 0x100
	s_addc_u32 s21, s21, 0
	s_add_u32 s41, s41, 0x100
	s_addc_u32 s42, s42, 0
	s_cmp_gt_u32 s43, 29
	s_barrier
	s_cbranch_scc0 .LBB0_1279
	v_lshl_add_u32 v146, s18, 8, v142
	v_lshl_or_b32 v140, s16, 8, v144
	v_ashrrev_i32_e32 v147, 31, v146
	v_ashrrev_i32_e32 v141, 31, v140
	v_lshlrev_b64 v[148:149], 14, v[146:147]
	v_max_f32_e32 v122, v122, v122
	v_max_f32_e32 v123, v123, v123
	v_lshl_add_u64 v[148:149], s[58:59], 0, v[148:149]
	v_lshlrev_b64 v[150:151], 1, v[140:141]
	v_max_f32_e32 v122, 0, v122
	v_max_f32_e32 v123, 0, v123
	v_lshl_add_u64 v[140:141], v[148:149], 0, v[150:151]
	v_pk_mul_f32 v[148:149], v[122:123], v[122:123]
	v_max_f32_e32 v123, v124, v124
	v_max_f32_e32 v126, v126, v126
	v_max_f32_e32 v127, v127, v127
	v_max_f32_e32 v122, v128, v128
	v_max_f32_e32 v124, 0, v123
	v_max_f32_e32 v123, v129, v129
	v_max_f32_e32 v125, v125, v125
	v_max_f32_e32 v126, 0, v126
	v_max_f32_e32 v127, 0, v127
	v_max_f32_e32 v122, 0, v122
	v_max_f32_e32 v123, 0, v123
	v_max_f32_e32 v125, 0, v125
	v_pk_mul_f32 v[126:127], v[126:127], v[126:127]
	v_pk_mul_f32 v[128:129], v[122:123], v[122:123]
	v_pk_mul_f32 v[152:153], v[124:125], v[124:125]
	v_max_f32_e32 v114, v114, v114
	v_max_f32_e32 v115, v115, v115
	v_cvt_pk_bf16_f32 v122, v126, v127
	v_cvt_pk_bf16_f32 v123, v128, v129
	v_cvt_pk_bf16_f32 v124, v148, v149
	v_cvt_pk_bf16_f32 v125, v152, v153
	v_max_f32_e32 v114, 0, v114
	v_max_f32_e32 v115, 0, v115
	global_store_dwordx4 v[140:141], v[122:125], off
	v_max_f32_e32 v118, v118, v118
	v_max_f32_e32 v119, v119, v119
	v_pk_mul_f32 v[122:123], v[114:115], v[114:115]
	v_max_f32_e32 v115, v116, v116
	v_max_f32_e32 v114, v120, v120
	v_max_f32_e32 v116, 0, v115
	v_max_f32_e32 v115, v121, v121
	v_max_f32_e32 v117, v117, v117
	v_max_f32_e32 v118, 0, v118
	v_max_f32_e32 v119, 0, v119
	v_max_f32_e32 v114, 0, v114
	v_max_f32_e32 v115, 0, v115
	v_max_f32_e32 v117, 0, v117
	v_pk_mul_f32 v[118:119], v[118:119], v[118:119]
	v_pk_mul_f32 v[120:121], v[114:115], v[114:115]
	v_pk_mul_f32 v[124:125], v[116:117], v[116:117]
	v_max_f32_e32 v106, v106, v106
	v_max_f32_e32 v107, v107, v107
	v_cvt_pk_bf16_f32 v114, v118, v119
	v_cvt_pk_bf16_f32 v115, v120, v121
	v_cvt_pk_bf16_f32 v116, v122, v123
	v_cvt_pk_bf16_f32 v117, v124, v125
	v_max_f32_e32 v106, 0, v106
	v_max_f32_e32 v107, 0, v107
	global_store_dwordx4 v[140:141], v[114:117], off offset:256
	v_max_f32_e32 v110, v110, v110
	v_max_f32_e32 v111, v111, v111
	v_or_b32_e32 v114, 16, v146
	v_pk_mul_f32 v[116:117], v[106:107], v[106:107]
	v_max_f32_e32 v107, v108, v108
	v_ashrrev_i32_e32 v115, 31, v114
	v_max_f32_e32 v106, v112, v112
	v_max_f32_e32 v108, 0, v107
	v_max_f32_e32 v107, v113, v113
	v_max_f32_e32 v109, v109, v109
	v_lshlrev_b64 v[114:115], 14, v[114:115]
	v_max_f32_e32 v110, 0, v110
	v_max_f32_e32 v111, 0, v111
	v_max_f32_e32 v106, 0, v106
	v_max_f32_e32 v107, 0, v107
	v_max_f32_e32 v109, 0, v109
	v_lshl_add_u64 v[114:115], s[58:59], 0, v[114:115]
	v_pk_mul_f32 v[110:111], v[110:111], v[110:111]
	v_pk_mul_f32 v[112:113], v[106:107], v[106:107]
	v_pk_mul_f32 v[118:119], v[108:109], v[108:109]
	v_max_f32_e32 v98, v98, v98
	v_max_f32_e32 v99, v99, v99
; __device__ __forceinline__ unsigned cvt_pk_bf16(float lo, float hi) { f32x2_t v = {lo, hi}; bf16x2_t b = __builtin_convertvector(v, bf16x2_t); return __builtin_bit_cast(unsigned, b); }
;     __device__ __forceinline__ void operator()(const f32x4 (&acc)[2][2][4][2], const pg8::Unit& u, int wr, int wc, int fr, int fq) const {
;     ...
;             for (int m = 0; m < 4; ++m) { const int row = row0 + ai * 128 + m * 16; bf16_t* rowp = O + (size_t)row * ldc + col0;
; #pragma unroll
;                 for (int bj = 0; bj < 2; ++bj) { f32x4 v0 = acc[ai][bj][m][0], v1 = acc[ai][bj][m][1];
;                     if (ACT == 1) {
; #pragma unroll
;                         for (int j = 0; j < 4; ++j) { float a = fmaxf(v0[j], 0.f), b = fmaxf(v1[j], 0.f); v0[j] = a * a; v1[j] = b * b; } }
;                     if (ACT == 0) { if (u.pn == (C_G / 256) && bj == 0 && wc == 0 && fq < 2) { float* gp = gate + (size_t)row * 16 + 8 * fq; *(f32x4*)gp = v0; *(f32x4*)(gp + 4) = v1; } }
;                     u32x4 w; w.x = cvt_pk_bf16(v0[0], v0[1]); w.y = cvt_pk_bf16(v0[2], v0[3]); w.z = cvt_pk_bf16(v1[0], v1[1]); w.w = cvt_pk_bf16(v1[2], v1[3]);
;                     *(u32x4*)(rowp + bj * 128) = w; } }
	v_lshl_add_u64 v[114:115], v[114:115], 0, v[150:151]
	v_cvt_pk_bf16_f32 v106, v110, v111
	v_cvt_pk_bf16_f32 v107, v112, v113
	v_cvt_pk_bf16_f32 v108, v116, v117
	v_cvt_pk_bf16_f32 v109, v118, v119
	v_max_f32_e32 v98, 0, v98
	v_max_f32_e32 v99, 0, v99
	global_store_dwordx4 v[114:115], v[106:109], off
	v_max_f32_e32 v102, v102, v102
	v_max_f32_e32 v103, v103, v103
	v_pk_mul_f32 v[106:107], v[98:99], v[98:99]
	v_max_f32_e32 v99, v100, v100
	v_max_f32_e32 v98, v104, v104
	v_max_f32_e32 v100, 0, v99
	v_max_f32_e32 v99, v105, v105
	v_max_f32_e32 v101, v101, v101
	v_max_f32_e32 v102, 0, v102
	v_max_f32_e32 v103, 0, v103
	v_max_f32_e32 v98, 0, v98
	v_max_f32_e32 v99, 0, v99
	v_max_f32_e32 v101, 0, v101
	v_pk_mul_f32 v[102:103], v[102:103], v[102:103]
	v_pk_mul_f32 v[104:105], v[98:99], v[98:99]
	v_pk_mul_f32 v[108:109], v[100:101], v[100:101]
	v_max_f32_e32 v90, v90, v90
	v_max_f32_e32 v91, v91, v91
	v_cvt_pk_bf16_f32 v98, v102, v103
	v_cvt_pk_bf16_f32 v99, v104, v105
	v_cvt_pk_bf16_f32 v100, v106, v107
	v_cvt_pk_bf16_f32 v101, v108, v109
	v_max_f32_e32 v90, 0, v90
	v_max_f32_e32 v91, 0, v91
	global_store_dwordx4 v[114:115], v[98:101], off offset:256
	v_max_f32_e32 v94, v94, v94
	v_max_f32_e32 v95, v95, v95
	v_or_b32_e32 v98, 32, v146
	v_pk_mul_f32 v[100:101], v[90:91], v[90:91]
	v_max_f32_e32 v91, v92, v92
	v_ashrrev_i32_e32 v99, 31, v98
	v_max_f32_e32 v90, v96, v96
	v_max_f32_e32 v92, 0, v91
	v_max_f32_e32 v91, v97, v97
	v_max_f32_e32 v93, v93, v93
	v_lshlrev_b64 v[98:99], 14, v[98:99]
	v_max_f32_e32 v94, 0, v94
	v_max_f32_e32 v95, 0, v95
	v_max_f32_e32 v90, 0, v90
	v_max_f32_e32 v91, 0, v91
	v_max_f32_e32 v93, 0, v93
	v_lshl_add_u64 v[98:99], s[58:59], 0, v[98:99]
	v_pk_mul_f32 v[94:95], v[94:95], v[94:95]
	v_pk_mul_f32 v[96:97], v[90:91], v[90:91]
	v_pk_mul_f32 v[102:103], v[92:93], v[92:93]
	v_max_f32_e32 v82, v82, v82
	v_max_f32_e32 v83, v83, v83
	v_lshl_add_u64 v[98:99], v[98:99], 0, v[150:151]
	v_cvt_pk_bf16_f32 v90, v94, v95
	v_cvt_pk_bf16_f32 v91, v96, v97
	v_cvt_pk_bf16_f32 v92, v100, v101
	v_cvt_pk_bf16_f32 v93, v102, v103
	v_max_f32_e32 v82, 0, v82
	v_max_f32_e32 v83, 0, v83
	global_store_dwordx4 v[98:99], v[90:93], off
	v_max_f32_e32 v86, v86, v86
	v_max_f32_e32 v87, v87, v87
	v_pk_mul_f32 v[90:91], v[82:83], v[82:83]
	v_max_f32_e32 v83, v84, v84
	v_max_f32_e32 v82, v88, v88
	v_max_f32_e32 v84, 0, v83
	v_max_f32_e32 v83, v89, v89
	v_max_f32_e32 v85, v85, v85
	v_max_f32_e32 v86, 0, v86
	v_max_f32_e32 v87, 0, v87
	v_max_f32_e32 v82, 0, v82
	v_max_f32_e32 v83, 0, v83
	v_max_f32_e32 v85, 0, v85
	v_pk_mul_f32 v[86:87], v[86:87], v[86:87]
	v_pk_mul_f32 v[88:89], v[82:83], v[82:83]
	v_pk_mul_f32 v[92:93], v[84:85], v[84:85]
	v_max_f32_e32 v74, v74, v74
	v_max_f32_e32 v75, v75, v75
	v_cvt_pk_bf16_f32 v82, v86, v87
	v_cvt_pk_bf16_f32 v83, v88, v89
	v_cvt_pk_bf16_f32 v84, v90, v91
	v_cvt_pk_bf16_f32 v85, v92, v93
	v_max_f32_e32 v74, 0, v74
	v_max_f32_e32 v75, 0, v75
	global_store_dwordx4 v[98:99], v[82:85], off offset:256
	v_max_f32_e32 v78, v78, v78
	v_max_f32_e32 v79, v79, v79
	v_or_b32_e32 v82, 48, v146
	v_pk_mul_f32 v[84:85], v[74:75], v[74:75]
	v_max_f32_e32 v75, v76, v76
	v_ashrrev_i32_e32 v83, 31, v82
	v_max_f32_e32 v74, v80, v80
	v_max_f32_e32 v76, 0, v75
	v_max_f32_e32 v75, v81, v81
	v_max_f32_e32 v77, v77, v77
	v_lshlrev_b64 v[82:83], 14, v[82:83]
	v_max_f32_e32 v78, 0, v78
	v_max_f32_e32 v79, 0, v79
	v_max_f32_e32 v74, 0, v74
	v_max_f32_e32 v75, 0, v75
	v_max_f32_e32 v77, 0, v77
	v_lshl_add_u64 v[82:83], s[58:59], 0, v[82:83]
	v_pk_mul_f32 v[78:79], v[78:79], v[78:79]
	v_pk_mul_f32 v[80:81], v[74:75], v[74:75]
	v_pk_mul_f32 v[86:87], v[76:77], v[76:77]
	v_max_f32_e32 v66, v66, v66
	v_max_f32_e32 v67, v67, v67
	v_lshl_add_u64 v[82:83], v[82:83], 0, v[150:151]
	v_cvt_pk_bf16_f32 v74, v78, v79
	v_cvt_pk_bf16_f32 v75, v80, v81
	v_cvt_pk_bf16_f32 v76, v84, v85
	v_cvt_pk_bf16_f32 v77, v86, v87
	v_max_f32_e32 v66, 0, v66
	v_max_f32_e32 v67, 0, v67
	global_store_dwordx4 v[82:83], v[74:77], off
	v_max_f32_e32 v70, v70, v70
	v_max_f32_e32 v71, v71, v71
	v_pk_mul_f32 v[74:75], v[66:67], v[66:67]
	v_max_f32_e32 v67, v68, v68
	v_max_f32_e32 v66, v72, v72
	v_max_f32_e32 v68, 0, v67
	v_max_f32_e32 v67, v73, v73
	v_max_f32_e32 v69, v69, v69
	v_max_f32_e32 v70, 0, v70
	v_max_f32_e32 v71, 0, v71
	v_max_f32_e32 v66, 0, v66
	v_max_f32_e32 v67, 0, v67
	v_max_f32_e32 v69, 0, v69
	v_pk_mul_f32 v[70:71], v[70:71], v[70:71]
	v_pk_mul_f32 v[72:73], v[66:67], v[66:67]
	v_pk_mul_f32 v[76:77], v[68:69], v[68:69]
	v_max_f32_e32 v58, v58, v58
	v_max_f32_e32 v59, v59, v59
	v_cvt_pk_bf16_f32 v66, v70, v71
	v_cvt_pk_bf16_f32 v67, v72, v73
	v_cvt_pk_bf16_f32 v68, v74, v75
	v_cvt_pk_bf16_f32 v69, v76, v77
	v_max_f32_e32 v58, 0, v58
	v_max_f32_e32 v59, 0, v59
	global_store_dwordx4 v[82:83], v[66:69], off offset:256
	v_max_f32_e32 v62, v62, v62
	v_max_f32_e32 v63, v63, v63
	v_pk_mul_f32 v[68:69], v[58:59], v[58:59]
	v_max_f32_e32 v59, v60, v60
	v_max_f32_e32 v62, 0, v62
	v_max_f32_e32 v63, 0, v63
	v_max_f32_e32 v58, v64, v64
	v_max_f32_e32 v60, 0, v59
	v_max_f32_e32 v59, v65, v65
	v_max_f32_e32 v61, v61, v61
	v_pk_mul_f32 v[62:63], v[62:63], v[62:63]
	v_max_f32_e32 v58, 0, v58
	v_max_f32_e32 v59, 0, v59
	v_max_f32_e32 v61, 0, v61
	s_mov_b32 s3, 0x200000
	v_pk_mul_f32 v[64:65], v[58:59], v[58:59]
	v_pk_mul_f32 v[70:71], v[60:61], v[60:61]
	v_cvt_pk_bf16_f32 v58, v62, v63
	v_add_co_u32_e32 v62, vcc, s3, v140
	v_max_f32_e32 v50, v50, v50
	v_max_f32_e32 v51, v51, v51
	v_cvt_pk_bf16_f32 v59, v64, v65
	v_cvt_pk_bf16_f32 v60, v68, v69
	v_cvt_pk_bf16_f32 v61, v70, v71
	v_addc_co_u32_e32 v63, vcc, 0, v141, vcc
	v_max_f32_e32 v50, 0, v50
	v_max_f32_e32 v51, 0, v51
; __device__ __forceinline__ unsigned cvt_pk_bf16(float lo, float hi) { f32x2_t v = {lo, hi}; bf16x2_t b = __builtin_convertvector(v, bf16x2_t); return __builtin_bit_cast(unsigned, b); }
; #define PG8_WAIT_V(n) asm volatile("s_waitcnt vmcnt(" #n ")" ::: "memory")
; #define PG8_BAR __builtin_amdgcn_s_barrier()
; template <class Epi, class Sched>
; __device__ __forceinline__ void gemm_phase(LAS unsigned char* lds, const Gemm g, const Sched& S, const Epi& E) {
;     ...
;         cur = nxt; cA = nA; cB = nB; ++ui;
;     }
;     PG8_WAIT_V(0);
;     if (wr == 0) PG8_BAR;
;     __device__ __forceinline__ void operator()(const f32x4 (&acc)[2][2][4][2], const pg8::Unit& u, int wr, int wc, int fr, int fq) const {
;     ...
;             for (int m = 0; m < 4; ++m) { const int row = row0 + ai * 128 + m * 16; bf16_t* rowp = O + (size_t)row * ldc + col0;
; #pragma unroll
;                 for (int bj = 0; bj < 2; ++bj) { f32x4 v0 = acc[ai][bj][m][0], v1 = acc[ai][bj][m][1];
;                     if (ACT == 1) {
; #pragma unroll
;                         for (int j = 0; j < 4; ++j) { float a = fmaxf(v0[j], 0.f), b = fmaxf(v1[j], 0.f); v0[j] = a * a; v1[j] = b * b; } }
;                     if (ACT == 0) { if (u.pn == (C_G / 256) && bj == 0 && wc == 0 && fq < 2) { float* gp = gate + (size_t)row * 16 + 8 * fq; *(f32x4*)gp = v0; *(f32x4*)(gp + 4) = v1; } }
;                     u32x4 w; w.x = cvt_pk_bf16(v0[0], v0[1]); w.y = cvt_pk_bf16(v0[2], v0[3]); w.z = cvt_pk_bf16(v1[0], v1[1]); w.w = cvt_pk_bf16(v1[2], v1[3]);
;                     *(u32x4*)(rowp + bj * 128) = w; } }
	global_store_dwordx4 v[62:63], v[58:61], off
	v_max_f32_e32 v54, v54, v54
	v_max_f32_e32 v55, v55, v55
	v_pk_mul_f32 v[58:59], v[50:51], v[50:51]
	v_max_f32_e32 v51, v52, v52
	v_max_f32_e32 v50, v56, v56
	v_max_f32_e32 v52, 0, v51
	v_max_f32_e32 v51, v57, v57
	v_max_f32_e32 v53, v53, v53
	v_max_f32_e32 v54, 0, v54
	v_max_f32_e32 v55, 0, v55
	v_max_f32_e32 v50, 0, v50
	v_max_f32_e32 v51, 0, v51
	v_max_f32_e32 v53, 0, v53
	s_mov_b64 s[20:21], 0x200000
	v_pk_mul_f32 v[54:55], v[54:55], v[54:55]
	v_pk_mul_f32 v[56:57], v[50:51], v[50:51]
	v_pk_mul_f32 v[60:61], v[52:53], v[52:53]
	v_max_f32_e32 v42, v42, v42
	v_max_f32_e32 v43, v43, v43
	v_lshl_add_u64 v[66:67], v[140:141], 0, s[20:21]
	v_cvt_pk_bf16_f32 v50, v54, v55
	v_cvt_pk_bf16_f32 v51, v56, v57
	v_cvt_pk_bf16_f32 v52, v58, v59
	v_cvt_pk_bf16_f32 v53, v60, v61
	v_max_f32_e32 v42, 0, v42
	v_max_f32_e32 v43, 0, v43
	global_store_dwordx4 v[66:67], v[50:53], off offset:256
	v_max_f32_e32 v46, v46, v46
	v_max_f32_e32 v47, v47, v47
	v_pk_mul_f32 v[52:53], v[42:43], v[42:43]
	v_max_f32_e32 v43, v44, v44
	v_max_f32_e32 v46, 0, v46
	v_max_f32_e32 v47, 0, v47
	v_max_f32_e32 v42, v48, v48
	v_max_f32_e32 v44, 0, v43
	v_max_f32_e32 v43, v49, v49
	v_max_f32_e32 v45, v45, v45
	v_pk_mul_f32 v[46:47], v[46:47], v[46:47]
	v_max_f32_e32 v42, 0, v42
	v_max_f32_e32 v43, 0, v43
	v_max_f32_e32 v45, 0, v45
	s_mov_b32 s3, 0x240000
	v_pk_mul_f32 v[48:49], v[42:43], v[42:43]
	v_pk_mul_f32 v[54:55], v[44:45], v[44:45]
	v_cvt_pk_bf16_f32 v42, v46, v47
	v_add_co_u32_e32 v46, vcc, s3, v140
	v_max_f32_e32 v34, v34, v34
	v_max_f32_e32 v35, v35, v35
	v_cvt_pk_bf16_f32 v43, v48, v49
	v_cvt_pk_bf16_f32 v44, v52, v53
	v_cvt_pk_bf16_f32 v45, v54, v55
	v_addc_co_u32_e32 v47, vcc, 0, v141, vcc
	v_max_f32_e32 v34, 0, v34
	v_max_f32_e32 v35, 0, v35
	global_store_dwordx4 v[46:47], v[42:45], off
	v_max_f32_e32 v38, v38, v38
	v_max_f32_e32 v39, v39, v39
	v_pk_mul_f32 v[42:43], v[34:35], v[34:35]
	v_max_f32_e32 v35, v36, v36
	v_max_f32_e32 v34, v40, v40
	v_max_f32_e32 v36, 0, v35
	v_max_f32_e32 v35, v41, v41
	v_max_f32_e32 v37, v37, v37
	v_max_f32_e32 v38, 0, v38
	v_max_f32_e32 v39, 0, v39
	v_max_f32_e32 v34, 0, v34
	v_max_f32_e32 v35, 0, v35
	v_max_f32_e32 v37, 0, v37
	s_mov_b64 s[20:21], 0x240000
	v_pk_mul_f32 v[38:39], v[38:39], v[38:39]
	v_pk_mul_f32 v[40:41], v[34:35], v[34:35]
	v_pk_mul_f32 v[44:45], v[36:37], v[36:37]
	v_max_f32_e32 v26, v26, v26
	v_max_f32_e32 v27, v27, v27
	v_lshl_add_u64 v[50:51], v[140:141], 0, s[20:21]
	v_cvt_pk_bf16_f32 v34, v38, v39
	v_cvt_pk_bf16_f32 v35, v40, v41
	v_cvt_pk_bf16_f32 v36, v42, v43
	v_cvt_pk_bf16_f32 v37, v44, v45
	v_max_f32_e32 v26, 0, v26
	v_max_f32_e32 v27, 0, v27
	global_store_dwordx4 v[50:51], v[34:37], off offset:256
	v_max_f32_e32 v30, v30, v30
	v_max_f32_e32 v31, v31, v31
	v_pk_mul_f32 v[36:37], v[26:27], v[26:27]
	v_max_f32_e32 v27, v28, v28
	v_max_f32_e32 v30, 0, v30
	v_max_f32_e32 v31, 0, v31
	v_max_f32_e32 v26, v32, v32
	v_max_f32_e32 v28, 0, v27
	v_max_f32_e32 v27, v33, v33
	v_max_f32_e32 v29, v29, v29
	v_pk_mul_f32 v[30:31], v[30:31], v[30:31]
	v_max_f32_e32 v26, 0, v26
	v_max_f32_e32 v27, 0, v27
	v_max_f32_e32 v29, 0, v29
	s_mov_b32 s3, 0x280000
	v_pk_mul_f32 v[32:33], v[26:27], v[26:27]
	v_pk_mul_f32 v[38:39], v[28:29], v[28:29]
	v_cvt_pk_bf16_f32 v26, v30, v31
	v_add_co_u32_e32 v30, vcc, s3, v140
	v_max_f32_e32 v18, v18, v18
	v_max_f32_e32 v19, v19, v19
	v_cvt_pk_bf16_f32 v27, v32, v33
	v_cvt_pk_bf16_f32 v28, v36, v37
	v_cvt_pk_bf16_f32 v29, v38, v39
	v_addc_co_u32_e32 v31, vcc, 0, v141, vcc
	v_max_f32_e32 v18, 0, v18
	v_max_f32_e32 v19, 0, v19
	global_store_dwordx4 v[30:31], v[26:29], off
	v_max_f32_e32 v22, v22, v22
	v_max_f32_e32 v23, v23, v23
	v_pk_mul_f32 v[26:27], v[18:19], v[18:19]
	v_max_f32_e32 v19, v20, v20
	v_max_f32_e32 v18, v24, v24
	v_max_f32_e32 v20, 0, v19
	v_max_f32_e32 v19, v25, v25
	v_max_f32_e32 v21, v21, v21
	v_max_f32_e32 v22, 0, v22
	v_max_f32_e32 v23, 0, v23
	v_max_f32_e32 v18, 0, v18
	v_max_f32_e32 v19, 0, v19
	v_max_f32_e32 v21, 0, v21
	s_mov_b64 s[20:21], 0x280000
	v_pk_mul_f32 v[22:23], v[22:23], v[22:23]
	v_pk_mul_f32 v[24:25], v[18:19], v[18:19]
	v_pk_mul_f32 v[28:29], v[20:21], v[20:21]
	v_max_f32_e32 v10, v10, v10
	v_max_f32_e32 v11, v11, v11
	v_lshl_add_u64 v[34:35], v[140:141], 0, s[20:21]
	v_cvt_pk_bf16_f32 v18, v22, v23
	v_cvt_pk_bf16_f32 v19, v24, v25
	v_cvt_pk_bf16_f32 v20, v26, v27
	v_cvt_pk_bf16_f32 v21, v28, v29
	v_max_f32_e32 v10, 0, v10
	v_max_f32_e32 v11, 0, v11
	global_store_dwordx4 v[34:35], v[18:21], off offset:256
	v_max_f32_e32 v14, v14, v14
	v_max_f32_e32 v15, v15, v15
	v_pk_mul_f32 v[20:21], v[10:11], v[10:11]
	v_max_f32_e32 v11, v12, v12
	v_max_f32_e32 v14, 0, v14
	v_max_f32_e32 v15, 0, v15
	v_max_f32_e32 v10, v16, v16
	v_max_f32_e32 v12, 0, v11
	v_max_f32_e32 v11, v17, v17
	v_max_f32_e32 v13, v13, v13
	v_pk_mul_f32 v[14:15], v[14:15], v[14:15]
	v_max_f32_e32 v10, 0, v10
	v_max_f32_e32 v11, 0, v11
	v_max_f32_e32 v13, 0, v13
	s_mov_b32 s3, 0x2c0000
	v_pk_mul_f32 v[16:17], v[10:11], v[10:11]
	v_pk_mul_f32 v[22:23], v[12:13], v[12:13]
	v_cvt_pk_bf16_f32 v10, v14, v15
	v_add_co_u32_e32 v14, vcc, s3, v140
	v_max_f32_e32 v2, v2, v2
	v_max_f32_e32 v3, v3, v3
	v_cvt_pk_bf16_f32 v11, v16, v17
	v_cvt_pk_bf16_f32 v12, v20, v21
	v_cvt_pk_bf16_f32 v13, v22, v23
	v_addc_co_u32_e32 v15, vcc, 0, v141, vcc
	v_max_f32_e32 v2, 0, v2
	v_max_f32_e32 v3, 0, v3
	global_store_dwordx4 v[14:15], v[10:13], off
	v_max_f32_e32 v6, v6, v6
	v_max_f32_e32 v7, v7, v7
	v_pk_mul_f32 v[10:11], v[2:3], v[2:3]
	v_max_f32_e32 v3, v4, v4
	v_max_f32_e32 v2, v8, v8
	v_max_f32_e32 v4, 0, v3
	v_max_f32_e32 v3, v9, v9
	v_max_f32_e32 v5, v5, v5
	v_max_f32_e32 v6, 0, v6
	v_max_f32_e32 v7, 0, v7
	v_max_f32_e32 v2, 0, v2
	v_max_f32_e32 v3, 0, v3
	v_max_f32_e32 v5, 0, v5
	s_mov_b64 s[20:21], 0x2c0000
	v_pk_mul_f32 v[6:7], v[6:7], v[6:7]
	v_pk_mul_f32 v[8:9], v[2:3], v[2:3]
	v_pk_mul_f32 v[12:13], v[4:5], v[4:5]
	v_lshl_add_u64 v[18:19], v[140:141], 0, s[20:21]
	v_cvt_pk_bf16_f32 v2, v6, v7
	v_cvt_pk_bf16_f32 v3, v8, v9
	v_cvt_pk_bf16_f32 v4, v10, v11
	v_cvt_pk_bf16_f32 v5, v12, v13
	s_and_b64 vcc, exec, s[0:1]
	s_mov_b32 s16, s8
	s_mov_b32 s18, s10
	s_mov_b64 s[22:23], s[14:15]
	s_mov_b64 s[20:21], s[12:13]
	global_store_dwordx4 v[18:19], v[2:5], off offset:256
	s_cbranch_vccz .LBB0_1276
	s_waitcnt vmcnt(0)
	s_cmpk_gt_u32 s27, 0xff
	s_cbranch_scc1 .LBB0_1283
	s_barrier
